# rstd table fill split over both half-workgroups (on top of hoisted residual-epilogue loads, batched weight-conversion loads, batched conv fix-up)
# baseline (speedup 1.0000x reference)
.LBB0_133:
	s_mov_b64 s[6:7], s[84:85]
	s_load_dwordx2 s[6:7], s[6:7], 0x80
	v_mov_b32_e32 v0, v208
	s_movk_i32 s8, 0x200
	s_nop 0
	v_cmp_gt_i32_e32 vcc, s8, v0
	s_and_saveexec_b64 s[8:9], vcc
	s_cbranch_execz .LBB0_138
	s_waitcnt lgkmcnt(0)
	s_add_u32 s10, s6, 0x2f00000
	v_readlane_b32 s12, v254, 51
	s_addc_u32 s11, s7, 0
	s_nop 0
	v_readfirstlane_b32 s14, v0
	s_lshr_b32 s14, s14, 8
	v_and_b32_e32 v0, 0xff, v0
	v_lshl_add_u32 v1, v0, 2, s12
	s_lshl_b32 s15, s14, 10
	v_add_u32_e32 v1, s15, v1
	s_cmp_lg_u32 s14, 0
	s_cselect_b32 s14, s86, 0
	s_cselect_b32 s15, s87, 0
	s_add_u32 s12, s78, s14
	s_addc_u32 s13, s79, s15
	s_branch .LBB0_136

.LBB0_136:
	v_cmp_gt_i64_e32 vcc, s[12:13], v[168:169]
	s_mov_b64 s[14:15], -1
	s_cbranch_vccnz .LBB0_135
	s_ashr_i32 s14, s12, 31
	s_lshr_b32 s14, s14, 29
	s_add_i32 s14, s12, s14
	s_ashr_i32 s15, s14, 3
	s_and_b32 s14, s14, -8
	s_sub_i32 s14, s12, s14
	s_cmp_lt_i32 s14, 0
	s_movk_i32 s16, 0xa1
	s_cselect_b32 s16, s16, 0xa0
	s_mul_i32 s14, s14, s16
	s_add_i32 s14, s14, s15
	s_mul_hi_i32 s15, s14, 0x66666667
	s_lshr_b32 s16, s15, 31
	s_ashr_i32 s15, s15, 5
	s_add_i32 s15, s15, s16
	s_lshl_b32 s16, s15, 3
	s_sub_i32 s17, 0x80, s16
	s_min_i32 s17, s17, 8
	s_abs_i32 s17, s17
	v_cvt_f32_u32_e32 v3, s17
	s_sub_i32 s18, 0, s17
	s_mulk_i32 s15, 0x50
	s_sub_i32 s14, s14, s15
	v_rcp_iflag_f32_e32 v3, v3
	s_ashr_i32 s15, s14, 31
	s_abs_i32 s14, s14
	v_mul_f32_e32 v3, 0x4f7ffffe, v3
	v_cvt_u32_f32_e32 v3, v3
	s_nop 0
	v_readfirstlane_b32 s19, v3
	s_mul_i32 s18, s18, s19
	s_mul_hi_u32 s18, s19, s18
	s_add_i32 s19, s19, s18
	s_mul_hi_u32 s18, s14, s19
	s_mul_i32 s18, s18, s17
	s_sub_i32 s14, s14, s18
	s_sub_i32 s18, s14, s17
	s_cmp_ge_u32 s14, s17
	s_cselect_b32 s14, s18, s14
	s_sub_i32 s18, s14, s17
	s_cmp_ge_u32 s14, s17
	s_cselect_b32 s14, s18, s14
	s_xor_b32 s14, s14, s15
	s_sub_i32 s14, s14, s15
	s_add_i32 s16, s16, s14
	v_lshl_add_u32 v4, s16, 8, v0
	v_ashrrev_i32_e32 v5, 31, v4
	v_lshlrev_b64 v[4:5], 6, v[4:5]
	v_lshl_add_u64 v[16:17], s[10:11], 0, v[4:5]
	global_load_dwordx4 v[4:7], v[16:17], off
	global_load_dwordx4 v[8:11], v[16:17], off offset:32
	global_load_dwordx4 v[12:15], v[16:17], off offset:16
	s_nop 0
	global_load_dwordx4 v[16:19], v[16:17], off offset:48
	s_add_u32 s12, s12, s86
	s_addc_u32 s13, s13, s87
	s_add_u32 s12, s12, s86
	s_addc_u32 s13, s13, s87
	s_mov_b64 s[14:15], 0
	s_waitcnt vmcnt(3)
	v_mov_b32_e32 v20, v4
	s_waitcnt vmcnt(2)
	v_mov_b32_e32 v21, v8
	v_mov_b32_e32 v8, v5
	v_mov_b32_e32 v4, v6
	v_mov_b32_e32 v5, v10
	v_mov_b32_e32 v10, v7
	s_waitcnt vmcnt(1)
	v_mov_b32_e32 v6, v12
	s_waitcnt vmcnt(0)
	v_mov_b32_e32 v7, v16
	v_mov_b32_e32 v16, v13
	v_mov_b32_e32 v12, v14
	v_mov_b32_e32 v13, v18
	v_mov_b32_e32 v18, v15
	v_pk_add_f32 v[8:9], v[20:21], v[8:9]
	v_pk_add_f32 v[4:5], v[4:5], v[10:11]
	v_pk_add_f32 v[6:7], v[6:7], v[16:17]
	v_pk_add_f32 v[10:11], v[12:13], v[18:19]
	v_pk_add_f32 v[4:5], v[8:9], v[4:5]
	v_pk_add_f32 v[6:7], v[6:7], v[10:11]
	s_nop 0
	v_pk_add_f32 v[4:5], v[4:5], v[6:7]
	s_nop 0
	v_add_f32_e32 v3, v4, v5
	v_fmamk_f32 v3, v3, 0x3a800000, v209
	v_mul_f32_e32 v4, 0x4b800000, v3
	v_cmp_gt_f32_e32 vcc, s68, v3
	s_nop 1
	v_cndmask_b32_e32 v3, v3, v4, vcc
	v_rsq_f32_e32 v3, v3
	s_nop 0
	v_mul_f32_e32 v4, 0x45800000, v3
	v_cndmask_b32_e32 v3, v3, v4, vcc
	ds_write_b32 v1, v3
	v_add_u32_e32 v1, 0x800, v1
	s_branch .LBB0_135

.LBB0_665:
	s_or_b64 exec, exec, s[8:9]
	s_mov_b64 s[6:7], s[84:85]
	s_waitcnt lgkmcnt(0)
	s_barrier
	s_load_dwordx2 s[8:9], s[6:7], 0x80
	v_mov_b32_e32 v0, v208
	s_movk_i32 s6, 0x200
	s_nop 0
	v_cmp_gt_i32_e32 vcc, s6, v0
	s_and_saveexec_b64 s[10:11], vcc
	s_cbranch_execz .LBB0_670
	s_waitcnt lgkmcnt(0)
	s_add_u32 s12, s8, 0x2f00000
	v_readlane_b32 s6, v254, 51
	s_addc_u32 s13, s9, 0
	v_readfirstlane_b32 s16, v0
	s_lshr_b32 s16, s16, 8
	v_and_b32_e32 v0, 0xff, v0
	v_lshl_add_u32 v1, v0, 2, s6
	s_lshl_b32 s17, s16, 10
	v_add_u32_e32 v1, s17, v1
	s_cmp_lg_u32 s16, 0
	s_cselect_b32 s16, s86, 0
	s_cselect_b32 s17, s87, 0
	s_add_u32 s14, s78, s16
	s_addc_u32 s15, s79, s17
	s_branch .LBB0_668

.LBB0_668:
	v_cmp_gt_i64_e32 vcc, s[14:15], v[166:167]
	s_mov_b64 s[16:17], -1
	s_cbranch_vccnz .LBB0_667
	s_ashr_i32 s6, s14, 31
	s_lshr_b32 s6, s6, 29
	s_add_i32 s6, s14, s6
	s_ashr_i32 s7, s6, 3
	s_and_b32 s6, s6, -8
	s_sub_i32 s6, s14, s6
	s_cmp_lt_i32 s6, 0
	s_movk_i32 s16, 0x161
	s_cselect_b32 s16, s16, 0x160
	s_mul_i32 s6, s6, s16
	s_add_i32 s6, s6, s7
	s_mul_hi_i32 s7, s6, 0x2e8ba2e9
	s_lshr_b32 s16, s7, 31
	s_ashr_i32 s7, s7, 5
	s_add_i32 s7, s7, s16
	s_lshl_b32 s16, s7, 3
	s_sub_i32 s17, 0x80, s16
	s_min_i32 s17, s17, 8
	s_abs_i32 s17, s17
	v_cvt_f32_u32_e32 v3, s17
	s_sub_i32 s18, 0, s17
	s_mulk_i32 s7, 0xb0
	s_sub_i32 s6, s6, s7
	v_rcp_iflag_f32_e32 v3, v3
	s_ashr_i32 s7, s6, 31
	s_abs_i32 s6, s6
	v_mul_f32_e32 v3, 0x4f7ffffe, v3
	v_cvt_u32_f32_e32 v3, v3
	s_nop 0
	v_readfirstlane_b32 s19, v3
	s_mul_i32 s18, s18, s19
	s_mul_hi_u32 s18, s19, s18
	s_add_i32 s19, s19, s18
	s_mul_hi_u32 s18, s6, s19
	s_mul_i32 s18, s18, s17
	s_sub_i32 s6, s6, s18
	s_sub_i32 s18, s6, s17
	s_cmp_ge_u32 s6, s17
	s_cselect_b32 s6, s18, s6
	s_sub_i32 s18, s6, s17
	s_cmp_ge_u32 s6, s17
	s_cselect_b32 s6, s18, s6
	s_xor_b32 s6, s6, s7
	s_sub_i32 s6, s6, s7
	s_add_i32 s16, s16, s6
	v_lshl_add_u32 v4, s16, 8, v0
	v_ashrrev_i32_e32 v5, 31, v4
	v_lshlrev_b64 v[4:5], 6, v[4:5]
	v_lshl_add_u64 v[16:17], s[12:13], 0, v[4:5]
	global_load_dwordx4 v[4:7], v[16:17], off
	global_load_dwordx4 v[8:11], v[16:17], off offset:32
	global_load_dwordx4 v[12:15], v[16:17], off offset:16
	s_nop 0
	global_load_dwordx4 v[16:19], v[16:17], off offset:48
	s_add_u32 s14, s14, s86
	s_addc_u32 s15, s15, s87
	s_add_u32 s14, s14, s86
	s_addc_u32 s15, s15, s87
	s_mov_b64 s[16:17], 0
	s_waitcnt vmcnt(3)
	v_mov_b32_e32 v20, v4
	s_waitcnt vmcnt(2)
	v_mov_b32_e32 v21, v8
	v_mov_b32_e32 v8, v5
	v_mov_b32_e32 v4, v6
	v_mov_b32_e32 v5, v10
	v_mov_b32_e32 v10, v7
	s_waitcnt vmcnt(1)
	v_mov_b32_e32 v6, v12
	s_waitcnt vmcnt(0)
	v_mov_b32_e32 v7, v16
	v_mov_b32_e32 v16, v13
	v_mov_b32_e32 v12, v14
	v_mov_b32_e32 v13, v18
	v_mov_b32_e32 v18, v15
	v_pk_add_f32 v[8:9], v[20:21], v[8:9]
	v_pk_add_f32 v[4:5], v[4:5], v[10:11]
	v_pk_add_f32 v[6:7], v[6:7], v[16:17]
	v_pk_add_f32 v[10:11], v[12:13], v[18:19]
	v_pk_add_f32 v[4:5], v[8:9], v[4:5]
	v_pk_add_f32 v[6:7], v[6:7], v[10:11]
	s_nop 0
	v_pk_add_f32 v[4:5], v[4:5], v[6:7]
	s_nop 0
	v_add_f32_e32 v3, v4, v5
	v_fmamk_f32 v3, v3, 0x3a800000, v209
	v_mul_f32_e32 v4, 0x4b800000, v3
	v_cmp_gt_f32_e32 vcc, s68, v3
	s_nop 1
	v_cndmask_b32_e32 v3, v3, v4, vcc
	v_rsq_f32_e32 v3, v3
	s_nop 0
	v_mul_f32_e32 v4, 0x45800000, v3
	v_cndmask_b32_e32 v3, v3, v4, vcc
	ds_write_b32 v1, v3
	v_add_u32_e32 v1, 0x800, v1
	s_branch .LBB0_667
